# P8 final epilogue: the 8 row-statistic sc1 loads issued together after the panel wait; the per-group vmcnt(0) that also waited for the previous group's store acks removed
# speedup vs baseline: 1.0069x; 1.0009x over previous
.LBB0_1386:
	v_lshl_add_u64 v[8:9], v[144:145], 2, s[10:11]
	global_load_dwordx4 v[4:7], v[8:9], off offset:16
	global_load_dwordx4 v[12:15], v[8:9], off
	s_waitcnt lgkmcnt(0)
	global_load_dwordx4 v[0:3], v[8:9], off offset:528
	s_nop 0
	global_load_dwordx4 v[8:11], v[8:9], off offset:512
	s_nop 0
	global_load_dword v226, v[112:113], off sc1
	global_load_dword v227, v[158:159], off sc1
	global_load_dword v228, v[162:163], off sc1
	global_load_dword v229, v[166:167], off sc1
	global_load_dword v230, v[112:113], off offset:512 sc1
	global_load_dword v231, v[112:113], off offset:576 sc1
	global_load_dword v232, v[112:113], off offset:640 sc1
	global_load_dword v233, v[112:113], off offset:704 sc1
	v_lshl_add_u64 v[186:187], v[146:147], 2, s[48:49]
	s_waitcnt vmcnt(0)
	v_mov_b32_e32 v144, v226
	v_fmamk_f32 v144, v144, 0x3a000000, v195
	v_mul_f32_e32 v145, 0x4b800000, v144
	v_cmp_gt_f32_e32 vcc, s61, v144
	s_nop 1
	v_cndmask_b32_e32 v144, v144, v145, vcc
	v_rsq_f32_e32 v144, v144
	s_nop 0
	v_mul_f32_e32 v145, 0x45800000, v144
	v_cndmask_b32_e32 v144, v144, v145, vcc
	v_pk_mul_f32 v[122:123], v[122:123], v[144:145] op_sel_hi:[1,0]
	v_pk_mul_f32 v[124:125], v[124:125], v[144:145] op_sel_hi:[1,0]
	v_pk_mul_f32 v[146:147], v[116:117], v[144:145] op_sel_hi:[1,0]
	v_pk_mul_f32 v[120:121], v[120:121], v[144:145] op_sel_hi:[1,0]
	v_pk_mul_f32 v[126:127], v[126:127], v[144:145] op_sel_hi:[1,0]
	v_pk_mul_f32 v[196:197], v[114:115], v[144:145] op_sel_hi:[1,0]
	v_pk_mul_f32 v[148:149], v[148:149], v[144:145] op_sel_hi:[1,0]
	v_pk_mul_f32 v[144:145], v[118:119], v[144:145] op_sel_hi:[1,0]
	v_pk_mul_f32 v[116:117], v[14:15], v[124:125]
	v_pk_mul_f32 v[114:115], v[12:13], v[122:123]
	v_pk_mul_f32 v[120:121], v[6:7], v[120:121]
	v_pk_mul_f32 v[118:119], v[4:5], v[146:147]
	v_pk_mul_f32 v[124:125], v[10:11], v[196:197]
	v_pk_mul_f32 v[122:123], v[8:9], v[126:127]
	v_pk_mul_f32 v[146:147], v[2:3], v[144:145]
	v_pk_mul_f32 v[144:145], v[0:1], v[148:149]
	global_store_dwordx4 v[186:187], v[114:117], off
	global_store_dwordx4 v[186:187], v[118:121], off offset:16
	global_store_dwordx4 v[186:187], v[122:125], off offset:512
	global_store_dwordx4 v[186:187], v[144:147], off offset:528
	v_mov_b32_e32 v114, v227
	s_nop 1
	v_fmamk_f32 v114, v114, 0x3a000000, v195
	v_mul_f32_e32 v115, 0x4b800000, v114
	v_cmp_gt_f32_e32 vcc, s61, v114
	s_nop 1
	v_cndmask_b32_e32 v114, v114, v115, vcc
	v_rsq_f32_e32 v116, v114
	v_lshl_add_u64 v[114:115], v[150:151], 2, s[48:49]
	v_mul_f32_e32 v117, 0x45800000, v116
	v_cndmask_b32_e32 v116, v116, v117, vcc
	v_pk_mul_f32 v[106:107], v[106:107], v[116:117] op_sel_hi:[1,0]
	v_pk_mul_f32 v[108:109], v[108:109], v[116:117] op_sel_hi:[1,0]
	v_pk_mul_f32 v[100:101], v[100:101], v[116:117] op_sel_hi:[1,0]
	v_pk_mul_f32 v[104:105], v[104:105], v[116:117] op_sel_hi:[1,0]
	v_pk_mul_f32 v[118:119], v[96:97], v[116:117] op_sel_hi:[1,0]
	v_pk_mul_f32 v[120:121], v[98:99], v[116:117] op_sel_hi:[1,0]
	v_pk_mul_f32 v[122:123], v[110:111], v[116:117] op_sel_hi:[1,0]
	v_pk_mul_f32 v[110:111], v[102:103], v[116:117] op_sel_hi:[1,0]
	v_pk_mul_f32 v[98:99], v[14:15], v[108:109]
	v_pk_mul_f32 v[96:97], v[12:13], v[106:107]
	v_pk_mul_f32 v[102:103], v[6:7], v[104:105]
	v_pk_mul_f32 v[100:101], v[4:5], v[100:101]
	v_pk_mul_f32 v[106:107], v[10:11], v[120:121]
	v_pk_mul_f32 v[104:105], v[8:9], v[118:119]
	v_pk_mul_f32 v[110:111], v[2:3], v[110:111]
	v_pk_mul_f32 v[108:109], v[0:1], v[122:123]
	global_store_dwordx4 v[114:115], v[96:99], off
	global_store_dwordx4 v[114:115], v[100:103], off offset:16
	global_store_dwordx4 v[114:115], v[104:107], off offset:512
	global_store_dwordx4 v[114:115], v[108:111], off offset:528
	v_mov_b32_e32 v96, v228
	s_nop 1
	v_fmamk_f32 v96, v96, 0x3a000000, v195
	v_mul_f32_e32 v97, 0x4b800000, v96
	v_cmp_gt_f32_e32 vcc, s61, v96
	s_nop 1
	v_cndmask_b32_e32 v96, v96, v97, vcc
	v_rsq_f32_e32 v98, v96
	v_lshl_add_u64 v[96:97], v[156:157], 2, s[48:49]
	v_mul_f32_e32 v99, 0x45800000, v98
	v_cndmask_b32_e32 v98, v98, v99, vcc
	v_pk_mul_f32 v[90:91], v[90:91], v[98:99] op_sel_hi:[1,0]
	v_pk_mul_f32 v[92:93], v[92:93], v[98:99] op_sel_hi:[1,0]
	v_pk_mul_f32 v[84:85], v[84:85], v[98:99] op_sel_hi:[1,0]
	v_pk_mul_f32 v[88:89], v[88:89], v[98:99] op_sel_hi:[1,0]
	v_pk_mul_f32 v[100:101], v[80:81], v[98:99] op_sel_hi:[1,0]
	v_pk_mul_f32 v[102:103], v[82:83], v[98:99] op_sel_hi:[1,0]
	v_pk_mul_f32 v[104:105], v[94:95], v[98:99] op_sel_hi:[1,0]
	v_pk_mul_f32 v[94:95], v[86:87], v[98:99] op_sel_hi:[1,0]
	v_pk_mul_f32 v[82:83], v[14:15], v[92:93]
	v_pk_mul_f32 v[80:81], v[12:13], v[90:91]
	v_pk_mul_f32 v[86:87], v[6:7], v[88:89]
	v_pk_mul_f32 v[84:85], v[4:5], v[84:85]
	v_pk_mul_f32 v[90:91], v[10:11], v[102:103]
	v_pk_mul_f32 v[88:89], v[8:9], v[100:101]
	v_pk_mul_f32 v[94:95], v[2:3], v[94:95]
	v_pk_mul_f32 v[92:93], v[0:1], v[104:105]
	global_store_dwordx4 v[96:97], v[80:83], off
	global_store_dwordx4 v[96:97], v[84:87], off offset:16
	global_store_dwordx4 v[96:97], v[88:91], off offset:512
	global_store_dwordx4 v[96:97], v[92:95], off offset:528
	v_mov_b32_e32 v80, v229
	s_nop 1
	v_fmamk_f32 v80, v80, 0x3a000000, v195
	v_mul_f32_e32 v81, 0x4b800000, v80
	v_cmp_gt_f32_e32 vcc, s61, v80
	s_nop 1
	v_cndmask_b32_e32 v80, v80, v81, vcc
	v_rsq_f32_e32 v82, v80
	v_lshl_add_u64 v[80:81], v[160:161], 2, s[48:49]
	v_mul_f32_e32 v83, 0x45800000, v82
	v_cndmask_b32_e32 v82, v82, v83, vcc
	v_pk_mul_f32 v[74:75], v[74:75], v[82:83] op_sel_hi:[1,0]
	v_pk_mul_f32 v[76:77], v[76:77], v[82:83] op_sel_hi:[1,0]
	v_pk_mul_f32 v[68:69], v[68:69], v[82:83] op_sel_hi:[1,0]
	v_pk_mul_f32 v[72:73], v[72:73], v[82:83] op_sel_hi:[1,0]
	v_pk_mul_f32 v[84:85], v[64:65], v[82:83] op_sel_hi:[1,0]
	v_pk_mul_f32 v[86:87], v[66:67], v[82:83] op_sel_hi:[1,0]
	v_pk_mul_f32 v[88:89], v[78:79], v[82:83] op_sel_hi:[1,0]
	v_pk_mul_f32 v[78:79], v[70:71], v[82:83] op_sel_hi:[1,0]
	v_pk_mul_f32 v[66:67], v[14:15], v[76:77]
	v_pk_mul_f32 v[64:65], v[12:13], v[74:75]
	v_pk_mul_f32 v[70:71], v[6:7], v[72:73]
	v_pk_mul_f32 v[68:69], v[4:5], v[68:69]
	v_pk_mul_f32 v[74:75], v[10:11], v[86:87]
	v_pk_mul_f32 v[72:73], v[8:9], v[84:85]
	v_pk_mul_f32 v[78:79], v[2:3], v[78:79]
	v_pk_mul_f32 v[76:77], v[0:1], v[88:89]
	global_store_dwordx4 v[80:81], v[64:67], off
	global_store_dwordx4 v[80:81], v[68:71], off offset:16
	global_store_dwordx4 v[80:81], v[72:75], off offset:512
	global_store_dwordx4 v[80:81], v[76:79], off offset:528
	v_mov_b32_e32 v64, v230
	s_nop 1
	v_fmamk_f32 v64, v64, 0x3a000000, v195
	v_mul_f32_e32 v65, 0x4b800000, v64
	v_cmp_gt_f32_e32 vcc, s61, v64
	s_nop 1
	v_cndmask_b32_e32 v64, v64, v65, vcc
	v_rsq_f32_e32 v66, v64
	v_lshl_add_u64 v[64:65], v[164:165], 2, s[48:49]
	v_mul_f32_e32 v67, 0x45800000, v66
	v_cndmask_b32_e32 v66, v66, v67, vcc
	v_pk_mul_f32 v[58:59], v[58:59], v[66:67] op_sel_hi:[1,0]
	v_pk_mul_f32 v[60:61], v[60:61], v[66:67] op_sel_hi:[1,0]
	v_pk_mul_f32 v[68:69], v[48:49], v[66:67] op_sel_hi:[1,0]
	v_pk_mul_f32 v[52:53], v[52:53], v[66:67] op_sel_hi:[1,0]
	v_pk_mul_f32 v[56:57], v[56:57], v[66:67] op_sel_hi:[1,0]
	v_pk_mul_f32 v[70:71], v[50:51], v[66:67] op_sel_hi:[1,0]
	v_pk_mul_f32 v[72:73], v[62:63], v[66:67] op_sel_hi:[1,0]
	v_pk_mul_f32 v[62:63], v[54:55], v[66:67] op_sel_hi:[1,0]
	v_pk_mul_f32 v[50:51], v[14:15], v[60:61]
	v_pk_mul_f32 v[48:49], v[12:13], v[58:59]
	v_pk_mul_f32 v[54:55], v[6:7], v[52:53]
	v_pk_mul_f32 v[52:53], v[4:5], v[68:69]
	v_pk_mul_f32 v[58:59], v[10:11], v[70:71]
	v_pk_mul_f32 v[56:57], v[8:9], v[56:57]
	v_pk_mul_f32 v[62:63], v[2:3], v[62:63]
	v_pk_mul_f32 v[60:61], v[0:1], v[72:73]
	global_store_dwordx4 v[64:65], v[48:51], off
	global_store_dwordx4 v[64:65], v[52:55], off offset:16
	global_store_dwordx4 v[64:65], v[56:59], off offset:512
	global_store_dwordx4 v[64:65], v[60:63], off offset:528
	v_mov_b32_e32 v48, v231
	s_nop 1
	v_fmamk_f32 v48, v48, 0x3a000000, v195
	v_mul_f32_e32 v49, 0x4b800000, v48
	v_cmp_gt_f32_e32 vcc, s61, v48
	s_nop 1
	v_cndmask_b32_e32 v48, v48, v49, vcc
	v_rsq_f32_e32 v50, v48
	v_lshl_add_u64 v[48:49], v[168:169], 2, s[48:49]
	v_mul_f32_e32 v51, 0x45800000, v50
	v_cndmask_b32_e32 v50, v50, v51, vcc
	v_pk_mul_f32 v[42:43], v[42:43], v[50:51] op_sel_hi:[1,0]
	v_pk_mul_f32 v[44:45], v[44:45], v[50:51] op_sel_hi:[1,0]
	v_pk_mul_f32 v[52:53], v[32:33], v[50:51] op_sel_hi:[1,0]
	v_pk_mul_f32 v[36:37], v[36:37], v[50:51] op_sel_hi:[1,0]
	v_pk_mul_f32 v[40:41], v[40:41], v[50:51] op_sel_hi:[1,0]
	v_pk_mul_f32 v[54:55], v[34:35], v[50:51] op_sel_hi:[1,0]
	v_pk_mul_f32 v[56:57], v[46:47], v[50:51] op_sel_hi:[1,0]
	v_pk_mul_f32 v[46:47], v[38:39], v[50:51] op_sel_hi:[1,0]
	v_pk_mul_f32 v[34:35], v[14:15], v[44:45]
	v_pk_mul_f32 v[32:33], v[12:13], v[42:43]
	v_pk_mul_f32 v[38:39], v[6:7], v[36:37]
	v_pk_mul_f32 v[36:37], v[4:5], v[52:53]
	v_pk_mul_f32 v[42:43], v[10:11], v[54:55]
	v_pk_mul_f32 v[40:41], v[8:9], v[40:41]
	v_pk_mul_f32 v[46:47], v[2:3], v[46:47]
	v_pk_mul_f32 v[44:45], v[0:1], v[56:57]
	global_store_dwordx4 v[48:49], v[32:35], off
	global_store_dwordx4 v[48:49], v[36:39], off offset:16
	global_store_dwordx4 v[48:49], v[40:43], off offset:512
	global_store_dwordx4 v[48:49], v[44:47], off offset:528
	v_mov_b32_e32 v32, v232
	s_nop 1
	v_fmamk_f32 v32, v32, 0x3a000000, v195
	v_mul_f32_e32 v33, 0x4b800000, v32
	v_cmp_gt_f32_e32 vcc, s61, v32
	s_nop 1
	v_cndmask_b32_e32 v32, v32, v33, vcc
	v_rsq_f32_e32 v34, v32
	v_lshl_add_u64 v[32:33], v[170:171], 2, s[48:49]
	v_mul_f32_e32 v35, 0x45800000, v34
	v_cndmask_b32_e32 v34, v34, v35, vcc
	v_pk_mul_f32 v[26:27], v[26:27], v[34:35] op_sel_hi:[1,0]
	v_pk_mul_f32 v[28:29], v[28:29], v[34:35] op_sel_hi:[1,0]
	v_pk_mul_f32 v[36:37], v[16:17], v[34:35] op_sel_hi:[1,0]
	v_pk_mul_f32 v[20:21], v[20:21], v[34:35] op_sel_hi:[1,0]
	v_pk_mul_f32 v[24:25], v[24:25], v[34:35] op_sel_hi:[1,0]
	v_pk_mul_f32 v[38:39], v[18:19], v[34:35] op_sel_hi:[1,0]
	v_pk_mul_f32 v[40:41], v[30:31], v[34:35] op_sel_hi:[1,0]
	v_pk_mul_f32 v[30:31], v[22:23], v[34:35] op_sel_hi:[1,0]
	v_pk_mul_f32 v[18:19], v[14:15], v[28:29]
	v_pk_mul_f32 v[16:17], v[12:13], v[26:27]
	v_pk_mul_f32 v[22:23], v[6:7], v[20:21]
	v_pk_mul_f32 v[20:21], v[4:5], v[36:37]
	v_pk_mul_f32 v[26:27], v[10:11], v[38:39]
	v_pk_mul_f32 v[24:25], v[8:9], v[24:25]
	v_pk_mul_f32 v[30:31], v[2:3], v[30:31]
	v_pk_mul_f32 v[28:29], v[0:1], v[40:41]
	global_store_dwordx4 v[32:33], v[16:19], off
	global_store_dwordx4 v[32:33], v[20:23], off offset:16
	global_store_dwordx4 v[32:33], v[24:27], off offset:512
	global_store_dwordx4 v[32:33], v[28:31], off offset:528
	v_mov_b32_e32 v18, v233
	s_nop 1
	v_lshl_add_u64 v[16:17], v[152:153], 2, s[48:49]
	s_andn2_b64 vcc, exec, s[4:5]
	s_mov_b64 s[4:5], -1
	v_fmamk_f32 v18, v18, 0x3a000000, v195
	v_mul_f32_e32 v19, 0x4b800000, v18
	v_cmp_gt_f32_e64 s[8:9], s61, v18
	s_nop 1
	v_cndmask_b32_e64 v18, v18, v19, s[8:9]
	v_rsq_f32_e32 v18, v18
	s_nop 0
	v_mul_f32_e32 v19, 0x45800000, v18
	v_cndmask_b32_e64 v18, v18, v19, s[8:9]
	v_pk_mul_f32 v[20:21], v[172:173], v[18:19] op_sel_hi:[1,0]
	v_pk_mul_f32 v[22:23], v[176:177], v[18:19] op_sel_hi:[1,0]
	v_pk_mul_f32 v[24:25], v[154:155], v[18:19] op_sel_hi:[1,0]
	v_pk_mul_f32 v[26:27], v[174:175], v[18:19] op_sel_hi:[1,0]
	v_pk_mul_f32 v[28:29], v[178:179], v[18:19] op_sel_hi:[1,0]
	v_pk_mul_f32 v[30:31], v[182:183], v[18:19] op_sel_hi:[1,0]
	v_pk_mul_f32 v[32:33], v[180:181], v[18:19] op_sel_hi:[1,0]
	v_pk_mul_f32 v[18:19], v[184:185], v[18:19] op_sel_hi:[1,0]
	v_pk_mul_f32 v[14:15], v[14:15], v[22:23]
	v_pk_mul_f32 v[12:13], v[12:13], v[20:21]
	v_pk_mul_f32 v[6:7], v[6:7], v[26:27]
	v_pk_mul_f32 v[4:5], v[4:5], v[24:25]
	v_pk_mul_f32 v[10:11], v[10:11], v[30:31]
	v_pk_mul_f32 v[8:9], v[8:9], v[28:29]
	v_pk_mul_f32 v[2:3], v[2:3], v[18:19]
	v_pk_mul_f32 v[0:1], v[0:1], v[32:33]
	global_store_dwordx4 v[16:17], v[12:15], off
	global_store_dwordx4 v[16:17], v[4:7], off offset:16
	global_store_dwordx4 v[16:17], v[8:11], off offset:512
	global_store_dwordx4 v[16:17], v[0:3], off offset:528
	s_cbranch_vccnz .LBB0_1348
	s_andn2_b64 vcc, exec, s[14:15]
	s_cbranch_vccnz .LBB0_1347
	s_barrier
	s_branch .LBB0_1347
